# EpiRes K-loop as two per-wave-group copies with one barrier per load+MFMA pair (stagger barriers removed), padded so following code keeps its 256B alignment
# speedup vs baseline: 1.0153x; 1.0031x over previous
.LBB0_220:
	v_readlane_b32 s2, v236, 62
	s_mov_b32 s42, s2
	s_mov_b32 s38, s2
	v_readlane_b32 s2, v237, 13
	v_mov_b32_e32 v8, v190
	v_readlane_b32 s3, v237, 14
	s_andn2_b64 vcc, exec, s[2:3]
	v_readfirstlane_b32 s28, v8
	s_cbranch_vccnz .LBB0_254
	v_lshlrev_b32_e32 v0, 4, v8
	v_add_u32_e32 v2, 0x2000, v0
	s_waitcnt lgkmcnt(0)
	v_ashrrev_i32_e32 v3, 31, v2
	v_lshrrev_b32_e32 v3, 22, v3
	v_add_u32_e32 v3, v2, v3
	v_ashrrev_i32_e32 v3, 10, v3
	v_mul_i32_i24_e32 v4, 0x400, v3
	v_sub_u32_e32 v2, v2, v4
	v_lshrrev_b32_e32 v4, 4, v2
	v_bitop3_b32 v4, v4, v2, 32 bitop3:0x6c
	v_ashrrev_i32_e32 v2, 31, v4
	v_lshrrev_b32_e32 v2, 26, v2
	v_add_u32_e32 v5, v4, v2
	v_lshlrev_b32_e32 v6, 3, v3
	v_ashrrev_i32_e32 v2, 6, v5
	v_and_b32_e32 v6, -16, v6
	s_lshl_b32 s4, s97, 3
	v_readlane_b32 s27, v236, 12
	v_add_u32_e32 v6, v2, v6
	s_or_b32 s54, s4, s27
	v_and_b32_e32 v2, 3, v2
	s_mov_b32 s27, 0x7fffffe0
	v_lshrrev_b32_e32 v7, 2, v6
	v_lshlrev_b32_e32 v9, 1, v6
	v_and_or_b32 v2, v6, s27, v2
	v_and_b32_e32 v7, 4, v7
	v_and_b32_e32 v9, 24, v9
	v_or3_b32 v2, v2, v7, v9
	v_mul_lo_u32 v7, v2, s42
	v_lshlrev_b32_e32 v2, 5, v3
	v_and_b32_e32 v3, 0xc0, v5
	v_sub_u32_e32 v3, v4, v3
	v_ashrrev_i16_sdwa v3, v193, sext(v3) dst_sel:DWORD dst_unused:UNUSED_PAD src0_sel:DWORD src1_sel:BYTE_0
	v_and_b32_e32 v2, 32, v2
	v_bfe_i32 v3, v3, 0, 16
	v_add_u32_e32 v5, v2, v3
	v_mul_lo_u32 v4, v6, s38
	v_add_lshl_u32 v130, v7, v5, 1
	v_add_lshl_u32 v132, v5, v4, 1
	v_bfe_i32 v5, v8, 27, 1
	v_lshrrev_b32_e32 v5, 22, v5
	v_add_u32_e32 v5, v0, v5
	v_and_b32_e32 v5, 0xfffffc00, v5
	v_sub_u32_e32 v0, v0, v5
	v_lshrrev_b32_e32 v5, 4, v0
	v_ashrrev_i32_e32 v7, 31, v8
	v_bitop3_b32 v0, v5, v0, 32 bitop3:0x6c
	v_lshrrev_b32_e32 v7, 26, v7
	v_ashrrev_i32_e32 v5, 31, v0
	v_add_u32_e32 v7, v8, v7
	v_lshrrev_b32_e32 v5, 26, v5
	v_ashrrev_i32_e32 v7, 6, v7
	v_add_u32_e32 v6, v0, v5
	v_lshlrev_b32_e32 v9, 3, v7
	v_ashrrev_i32_e32 v5, 6, v6
	v_and_b32_e32 v9, -16, v9
	v_add_u32_e32 v9, v5, v9
	v_and_b32_e32 v5, 3, v5
	v_lshrrev_b32_e32 v10, 2, v9
	s_waitcnt vmcnt(0)
	v_lshlrev_b32_e32 v11, 1, v9
	s_ashr_i32 s43, s42, 31
	v_and_or_b32 v5, v9, s27, v5
	v_and_b32_e32 v10, 4, v10
	v_and_b32_e32 v11, 24, v11
	v_readlane_b32 s40, v236, 24
	s_ashr_i32 s39, s38, 31
	s_lshl_b64 s[34:35], s[42:43], 9
	v_or3_b32 v5, v5, v10, v11
	v_readlane_b32 s41, v236, 25
	s_lshl_b64 s[2:3], s[38:39], 8
	v_mul_lo_u32 v10, v5, s42
	v_lshlrev_b32_e32 v5, 5, v7
	v_mul_lo_u32 v7, v9, s38
	s_mul_i32 s27, s34, s41
	s_mul_hi_u32 s38, s34, s40
	v_and_b32_e32 v6, 0xc0, v6
	s_add_i32 s27, s38, s27
	s_lshr_b64 s[38:39], s[42:43], 23
	s_ashr_i32 s44, s28, 6
	v_sub_u32_e32 v0, v0, v6
	s_ashr_i32 s55, s54, 31
	s_mul_i32 s38, s38, s40
	s_ashr_i32 s29, s28, 8
	s_lshl_b64 s[6:7], s[42:43], 8
	s_lshl_b32 s5, s44, 10
	v_ashrrev_i16_sdwa v0, v193, sext(v0) dst_sel:DWORD dst_unused:UNUSED_PAD src0_sel:DWORD src1_sel:BYTE_0
	s_lshl_b64 s[30:31], s[54:55], 21
	s_add_i32 s27, s27, s38
	s_mul_i32 s38, s34, s40
	v_readlane_b32 s39, v235, 4
	v_and_b32_e32 v5, 32, v5
	v_bfe_i32 v6, v0, 0, 16
	s_add_u32 s58, s39, s38
	v_readlane_b32 s38, v235, 6
	v_add_u32_e32 v11, v5, v6
	s_addc_u32 s59, s38, s27
	s_add_i32 s27, s5, 0
	v_add_lshl_u32 v0, v10, v11, 1
	s_add_i32 m0, s27, 0x10000
	v_readlane_b32 s38, v236, 61
	global_load_lds_dwordx4 v0, s[58:59]
	s_add_i32 m0, s27, 0x12000
	s_add_u32 s40, s58, s6
	global_load_lds_dwordx4 v130, s[58:59]
	s_addc_u32 s41, s59, s7
	s_add_i32 m0, s27, 0x14000
	v_add_lshl_u32 v134, v11, v7, 1
	global_load_lds_dwordx4 v0, s[40:41]
	s_add_i32 m0, s27, 0x16000
	s_add_u32 s56, s38, s30
	v_readlane_b32 s30, v236, 58
	s_addc_u32 s57, s30, s31
	s_add_i32 s30, s27, 0x2000
	global_load_lds_dwordx4 v130, s[40:41]
	s_mov_b32 m0, s27
	s_add_u32 s38, s56, s2
	global_load_lds_dwordx4 v134, s[56:57]
	s_mov_b32 m0, s30
	s_addc_u32 s39, s57, s3
	s_add_i32 s31, s27, 0x4000
	global_load_lds_dwordx4 v132, s[56:57]
	s_mov_b32 m0, s31
	s_add_i32 s53, s27, 0x6000
	global_load_lds_dwordx4 v134, s[38:39]
	s_mov_b32 m0, s53
	s_cmp_eq_u32 s29, 1
	global_load_lds_dwordx4 v132, s[38:39]
	s_cselect_b64 s[38:39], -1, 0
	s_cmp_lg_u32 s29, 1
	s_cbranch_scc1 .LBB0_223
	s_nop 0

.LBB0_228:
	s_and_b32 s48, s48, 7
	s_or_b32 s73, s48, s4
	s_and_b64 s[48:49], s[46:47], exec
	s_cselect_b32 s48, s73, s29
	s_ashr_i32 s49, s48, 31
	s_lshl_b64 s[48:49], s[48:49], 21
	v_readlane_b32 s29, v236, 61
	s_add_u32 s48, s29, s48
	v_readlane_b32 s29, v236, 58
	v_mov_b32_e32 v125, 0
	s_addc_u32 s49, s29, s49
	s_andn2_b64 vcc, exec, s[42:43]
	v_mov_b32_e32 v124, v125
	v_mov_b32_e32 v123, v125
	v_mov_b32_e32 v122, v125
	v_mov_b32_e32 v129, v125
	v_mov_b32_e32 v128, v125
	v_mov_b32_e32 v127, v125
	v_mov_b32_e32 v126, v125
	v_mov_b32_e32 v113, v125
	v_mov_b32_e32 v112, v125
	v_mov_b32_e32 v111, v125
	v_mov_b32_e32 v110, v125
	v_mov_b32_e32 v109, v125
	v_mov_b32_e32 v108, v125
	v_mov_b32_e32 v107, v125
	v_mov_b32_e32 v106, v125
	v_mov_b32_e32 v97, v125
	v_mov_b32_e32 v96, v125
	v_mov_b32_e32 v95, v125
	v_mov_b32_e32 v94, v125
	v_mov_b32_e32 v93, v125
	v_mov_b32_e32 v92, v125
	v_mov_b32_e32 v91, v125
	v_mov_b32_e32 v90, v125
	v_mov_b32_e32 v81, v125
	v_mov_b32_e32 v80, v125
	v_mov_b32_e32 v79, v125
	v_mov_b32_e32 v78, v125
	v_mov_b32_e32 v77, v125
	v_mov_b32_e32 v76, v125
	v_mov_b32_e32 v75, v125
	v_mov_b32_e32 v74, v125
	v_mov_b32_e32 v121, v125
	v_mov_b32_e32 v120, v125
	v_mov_b32_e32 v119, v125
	v_mov_b32_e32 v118, v125
	v_mov_b32_e32 v117, v125
	v_mov_b32_e32 v116, v125
	v_mov_b32_e32 v115, v125
	v_mov_b32_e32 v114, v125
	v_mov_b32_e32 v105, v125
	v_mov_b32_e32 v104, v125
	v_mov_b32_e32 v103, v125
	v_mov_b32_e32 v102, v125
	v_mov_b32_e32 v101, v125
	v_mov_b32_e32 v100, v125
	v_mov_b32_e32 v99, v125
	v_mov_b32_e32 v98, v125
	v_mov_b32_e32 v89, v125
	v_mov_b32_e32 v88, v125
	v_mov_b32_e32 v87, v125
	v_mov_b32_e32 v86, v125
	v_mov_b32_e32 v85, v125
	v_mov_b32_e32 v84, v125
	v_mov_b32_e32 v83, v125
	v_mov_b32_e32 v82, v125
	v_mov_b32_e32 v73, v125
	v_mov_b32_e32 v72, v125
	v_mov_b32_e32 v71, v125
	v_mov_b32_e32 v70, v125
	v_mov_b32_e32 v69, v125
	v_mov_b32_e32 v68, v125
	v_mov_b32_e32 v67, v125
	v_mov_b32_e32 v66, v125
	v_mov_b32_e32 v65, v125
	v_mov_b32_e32 v64, v125
	v_mov_b32_e32 v63, v125
	v_mov_b32_e32 v62, v125
	v_mov_b32_e32 v61, v125
	v_mov_b32_e32 v60, v125
	v_mov_b32_e32 v59, v125
	v_mov_b32_e32 v58, v125
	v_mov_b32_e32 v49, v125
	v_mov_b32_e32 v48, v125
	v_mov_b32_e32 v47, v125
	v_mov_b32_e32 v46, v125
	v_mov_b32_e32 v45, v125
	v_mov_b32_e32 v44, v125
	v_mov_b32_e32 v43, v125
	v_mov_b32_e32 v42, v125
	v_mov_b32_e32 v33, v125
	v_mov_b32_e32 v32, v125
	v_mov_b32_e32 v31, v125
	v_mov_b32_e32 v30, v125
	v_mov_b32_e32 v29, v125
	v_mov_b32_e32 v28, v125
	v_mov_b32_e32 v27, v125
	v_mov_b32_e32 v26, v125
	v_mov_b32_e32 v17, v125
	v_mov_b32_e32 v16, v125
	v_mov_b32_e32 v15, v125
	v_mov_b32_e32 v14, v125
	v_mov_b32_e32 v13, v125
	v_mov_b32_e32 v12, v125
	v_mov_b32_e32 v11, v125
	v_mov_b32_e32 v10, v125
	v_mov_b32_e32 v57, v125
	v_mov_b32_e32 v56, v125
	v_mov_b32_e32 v55, v125
	v_mov_b32_e32 v54, v125
	v_mov_b32_e32 v53, v125
	v_mov_b32_e32 v52, v125
	v_mov_b32_e32 v51, v125
	v_mov_b32_e32 v50, v125
	v_mov_b32_e32 v41, v125
	v_mov_b32_e32 v40, v125
	v_mov_b32_e32 v39, v125
	v_mov_b32_e32 v38, v125
	v_mov_b32_e32 v37, v125
	v_mov_b32_e32 v36, v125
	v_mov_b32_e32 v35, v125
	v_mov_b32_e32 v34, v125
	v_mov_b32_e32 v25, v125
	v_mov_b32_e32 v24, v125
	v_mov_b32_e32 v23, v125
	v_mov_b32_e32 v22, v125
	v_mov_b32_e32 v21, v125
	v_mov_b32_e32 v20, v125
	v_mov_b32_e32 v19, v125
	v_mov_b32_e32 v18, v125
	v_mov_b32_e32 v9, v125
	v_mov_b32_e32 v8, v125
	v_mov_b32_e32 v7, v125
	v_mov_b32_e32 v6, v125
	v_mov_b32_e32 v5, v125
	v_mov_b32_e32 v4, v125
	s_waitcnt lgkmcnt(0)
	v_mov_b32_e32 v3, v125
	v_mov_b32_e32 v2, v125
	s_cbranch_vccnz .LBB0_232
	s_and_b64 s[50:51], s[46:47], exec
	s_cselect_b32 s29, s49, s57
	s_cselect_b32 s50, s48, s56
	s_add_u32 s56, s56, 0x80
	s_addc_u32 s57, s57, 0
	s_add_u32 s51, s58, 0x100
	v_mov_b32_e32 v2, 0
	s_addc_u32 s55, s59, 0
	s_mov_b32 s58, 0
	v_mov_b32_e32 v3, v2
	v_mov_b32_e32 v4, v2
	v_mov_b32_e32 v5, v2
	v_mov_b32_e32 v6, v2
	v_mov_b32_e32 v7, v2
	v_mov_b32_e32 v8, v2
	v_mov_b32_e32 v9, v2
	v_mov_b32_e32 v18, v2
	v_mov_b32_e32 v19, v2
	v_mov_b32_e32 v20, v2
	v_mov_b32_e32 v21, v2
	v_mov_b32_e32 v22, v2
	v_mov_b32_e32 v23, v2
	v_mov_b32_e32 v24, v2
	v_mov_b32_e32 v25, v2
	v_mov_b32_e32 v34, v2
	v_mov_b32_e32 v35, v2
	v_mov_b32_e32 v36, v2
	v_mov_b32_e32 v37, v2
	v_mov_b32_e32 v38, v2
	v_mov_b32_e32 v39, v2
	v_mov_b32_e32 v40, v2
	v_mov_b32_e32 v41, v2
	v_mov_b32_e32 v50, v2
	v_mov_b32_e32 v51, v2
	v_mov_b32_e32 v52, v2
	v_mov_b32_e32 v53, v2
	v_mov_b32_e32 v54, v2
	v_mov_b32_e32 v55, v2
	v_mov_b32_e32 v56, v2
	v_mov_b32_e32 v57, v2
	v_mov_b32_e32 v10, v2
	v_mov_b32_e32 v11, v2
	v_mov_b32_e32 v12, v2
	v_mov_b32_e32 v13, v2
	v_mov_b32_e32 v14, v2
	v_mov_b32_e32 v15, v2
	v_mov_b32_e32 v16, v2
	v_mov_b32_e32 v17, v2
	v_mov_b32_e32 v26, v2
	v_mov_b32_e32 v27, v2
	v_mov_b32_e32 v28, v2
	v_mov_b32_e32 v29, v2
	v_mov_b32_e32 v30, v2
	v_mov_b32_e32 v31, v2
	v_mov_b32_e32 v32, v2
	v_mov_b32_e32 v33, v2
	v_mov_b32_e32 v42, v2
	v_mov_b32_e32 v43, v2
	v_mov_b32_e32 v44, v2
	v_mov_b32_e32 v45, v2
	v_mov_b32_e32 v46, v2
	v_mov_b32_e32 v47, v2
	v_mov_b32_e32 v48, v2
	v_mov_b32_e32 v49, v2
	v_mov_b32_e32 v58, v2
	v_mov_b32_e32 v59, v2
	v_mov_b32_e32 v60, v2
	v_mov_b32_e32 v61, v2
	v_mov_b32_e32 v62, v2
	v_mov_b32_e32 v63, v2
	v_mov_b32_e32 v64, v2
	v_mov_b32_e32 v65, v2
	v_mov_b32_e32 v66, v2
	v_mov_b32_e32 v67, v2
	v_mov_b32_e32 v68, v2
	v_mov_b32_e32 v69, v2
	v_mov_b32_e32 v70, v2
	v_mov_b32_e32 v71, v2
	v_mov_b32_e32 v72, v2
	v_mov_b32_e32 v73, v2
	v_mov_b32_e32 v82, v2
	v_mov_b32_e32 v83, v2
	v_mov_b32_e32 v84, v2
	v_mov_b32_e32 v85, v2
	v_mov_b32_e32 v86, v2
	v_mov_b32_e32 v87, v2
	v_mov_b32_e32 v88, v2
	v_mov_b32_e32 v89, v2
	v_mov_b32_e32 v98, v2
	v_mov_b32_e32 v99, v2
	v_mov_b32_e32 v100, v2
	v_mov_b32_e32 v101, v2
	v_mov_b32_e32 v102, v2
	v_mov_b32_e32 v103, v2
	v_mov_b32_e32 v104, v2
	v_mov_b32_e32 v105, v2
	v_mov_b32_e32 v114, v2
	v_mov_b32_e32 v115, v2
	v_mov_b32_e32 v116, v2
	v_mov_b32_e32 v117, v2
	v_mov_b32_e32 v118, v2
	v_mov_b32_e32 v119, v2
	v_mov_b32_e32 v120, v2
	v_mov_b32_e32 v121, v2
	v_mov_b32_e32 v74, v2
	v_mov_b32_e32 v75, v2
	v_mov_b32_e32 v76, v2
	v_mov_b32_e32 v77, v2
	v_mov_b32_e32 v78, v2
	v_mov_b32_e32 v79, v2
	v_mov_b32_e32 v80, v2
	v_mov_b32_e32 v81, v2
	v_mov_b32_e32 v90, v2
	v_mov_b32_e32 v91, v2
	v_mov_b32_e32 v92, v2
	v_mov_b32_e32 v93, v2
	v_mov_b32_e32 v94, v2
	v_mov_b32_e32 v95, v2
	v_mov_b32_e32 v96, v2
	v_mov_b32_e32 v97, v2
	v_mov_b32_e32 v106, v2
	v_mov_b32_e32 v107, v2
	v_mov_b32_e32 v108, v2
	v_mov_b32_e32 v109, v2
	v_mov_b32_e32 v110, v2
	v_mov_b32_e32 v111, v2
	v_mov_b32_e32 v112, v2
	v_mov_b32_e32 v113, v2
	v_mov_b32_e32 v126, v2
	v_mov_b32_e32 v127, v2
	v_mov_b32_e32 v128, v2
	v_mov_b32_e32 v129, v2
	v_mov_b32_e32 v122, v2
	v_mov_b32_e32 v123, v2
	v_mov_b32_e32 v124, v2
	v_mov_b32_e32 v125, v2
	s_and_b64 vcc, exec, s[40:41]
	s_cbranch_vccz .Lmy_q230
.LBB0_230:
	s_add_i32 s74, s58, 2
	s_add_u32 s75, s56, 0x80
	s_addc_u32 s59, s57, 0
	s_add_i32 s78, 0, 0x10000
	s_cmp_eq_u32 s66, s58
	s_cselect_b32 s59, s29, s59
	s_cselect_b32 s58, s50, s75
	s_cselect_b32 s81, s45, s55
	s_cselect_b32 s80, s44, s51
	s_add_i32 s75, 0, 0x14000
	v_add_u32_e32 v156, s78, v146
	v_add_u32_e32 v172, s75, v146
	ds_read_b128 v[140:143], v156
	ds_read_b128 v[148:151], v156 offset:1024
	ds_read_b128 v[152:155], v156 offset:2048
	ds_read_b128 v[156:159], v156 offset:3072
	ds_read_b128 v[160:163], v172
	ds_read_b128 v[164:167], v172 offset:1024
	ds_read_b128 v[168:171], v172 offset:2048
	ds_read_b128 v[172:175], v172 offset:3072
	v_lshl_add_u64 v[188:189], s[56:57], 0, v[134:135]
	s_mov_b32 m0, s64
	s_nop 0
	global_load_lds_dwordx4 v[188:189], off
	v_lshl_add_u64 v[188:189], s[56:57], 0, v[132:133]
	s_mov_b32 m0, s65
	s_nop 0
	global_load_lds_dwordx4 v[188:189], off
	v_lshl_add_u64 v[188:189], s[56:57], 0, v[136:137]
	s_add_i32 m0, s27, 0xc000
	s_nop 0
	global_load_lds_dwordx4 v[188:189], off
	v_lshl_add_u64 v[188:189], s[56:57], 0, v[138:139]
	s_add_i32 m0, s27, 0xe000
	s_nop 0
	global_load_lds_dwordx4 v[188:189], off
	ds_read_b128 v[176:179], v147
	ds_read_b128 v[180:183], v147 offset:1024
	ds_read_b128 v[184:187], v147 offset:2048
	ds_read_b128 v[200:203], v147 offset:3072
	ds_read_b128 v[204:207], v147 offset:4096
	ds_read_b128 v[208:211], v147 offset:5120
	ds_read_b128 v[212:215], v147 offset:6144
	ds_read_b128 v[216:219], v147 offset:7168
	s_waitcnt vmcnt(8)
	s_waitcnt lgkmcnt(0)
	s_barrier
	s_setprio 1
	s_waitcnt lgkmcnt(0)
	v_mfma_f32_16x16x32_bf16 v[122:125], v[140:143], v[176:179], v[122:125]
	v_mfma_f32_16x16x32_bf16 v[126:129], v[152:155], v[176:179], v[126:129]
	v_mfma_f32_16x16x32_bf16 v[110:113], v[140:143], v[184:187], v[110:113]
	v_mfma_f32_16x16x32_bf16 v[106:109], v[152:155], v[184:187], v[106:109]
	v_mfma_f32_16x16x32_bf16 v[94:97], v[140:143], v[204:207], v[94:97]
	v_mfma_f32_16x16x32_bf16 v[90:93], v[152:155], v[204:207], v[90:93]
	v_mfma_f32_16x16x32_bf16 v[78:81], v[140:143], v[212:215], v[78:81]
	v_mfma_f32_16x16x32_bf16 v[74:77], v[152:155], v[212:215], v[74:77]
	v_mfma_f32_16x16x32_bf16 v[122:125], v[148:151], v[180:183], v[122:125]
	v_mfma_f32_16x16x32_bf16 v[126:129], v[156:159], v[180:183], v[126:129]
	v_mfma_f32_16x16x32_bf16 v[110:113], v[148:151], v[200:203], v[110:113]
	v_mfma_f32_16x16x32_bf16 v[106:109], v[156:159], v[200:203], v[106:109]
	v_mfma_f32_16x16x32_bf16 v[94:97], v[148:151], v[208:211], v[94:97]
	v_mfma_f32_16x16x32_bf16 v[90:93], v[156:159], v[208:211], v[90:93]
	v_mfma_f32_16x16x32_bf16 v[78:81], v[148:151], v[216:219], v[78:81]
	v_mfma_f32_16x16x32_bf16 v[74:77], v[156:159], v[216:219], v[74:77]
	s_setprio 0
	s_setprio 1
	v_mfma_f32_16x16x32_bf16 v[118:121], v[160:163], v[176:179], v[118:121]
	v_mfma_f32_16x16x32_bf16 v[114:117], v[168:171], v[176:179], v[114:117]
	v_mfma_f32_16x16x32_bf16 v[102:105], v[160:163], v[184:187], v[102:105]
	v_mfma_f32_16x16x32_bf16 v[98:101], v[168:171], v[184:187], v[98:101]
	v_mfma_f32_16x16x32_bf16 v[86:89], v[160:163], v[204:207], v[86:89]
	v_mfma_f32_16x16x32_bf16 v[82:85], v[168:171], v[204:207], v[82:85]
	v_mfma_f32_16x16x32_bf16 v[70:73], v[160:163], v[212:215], v[70:73]
	v_mfma_f32_16x16x32_bf16 v[66:69], v[168:171], v[212:215], v[66:69]
	v_mfma_f32_16x16x32_bf16 v[118:121], v[164:167], v[180:183], v[118:121]
	v_mfma_f32_16x16x32_bf16 v[114:117], v[172:175], v[180:183], v[114:117]
	v_mfma_f32_16x16x32_bf16 v[102:105], v[164:167], v[200:203], v[102:105]
	v_mfma_f32_16x16x32_bf16 v[98:101], v[172:175], v[200:203], v[98:101]
	v_mfma_f32_16x16x32_bf16 v[86:89], v[164:167], v[208:211], v[86:89]
	v_mfma_f32_16x16x32_bf16 v[82:85], v[172:175], v[208:211], v[82:85]
	v_mfma_f32_16x16x32_bf16 v[70:73], v[164:167], v[216:219], v[70:73]
	v_mfma_f32_16x16x32_bf16 v[66:69], v[172:175], v[216:219], v[66:69]
	s_setprio 0
	s_add_i32 s78, s78, s5
	v_lshl_add_u64 v[188:189], s[80:81], 0, v[0:1]
	s_mov_b32 m0, s78
	ds_read_b128 v[176:179], v147 offset:16384
	ds_read_b128 v[180:183], v147 offset:17408
	ds_read_b128 v[184:187], v147 offset:18432
	ds_read_b128 v[200:203], v147 offset:19456
	ds_read_b128 v[204:207], v147 offset:20480
	ds_read_b128 v[208:211], v147 offset:21504
	ds_read_b128 v[212:215], v147 offset:22528
	ds_read_b128 v[216:219], v147 offset:23552
	global_load_lds_dwordx4 v[188:189], off
	s_add_i32 m0, s78, 0x2000
	v_lshl_add_u64 v[220:221], s[80:81], 0, v[130:131]
	s_add_u32 s80, s80, s6
	s_addc_u32 s81, s81, s7
	s_add_i32 s75, s75, s5
	global_load_lds_dwordx4 v[220:221], off
	v_lshl_add_u64 v[222:223], s[80:81], 0, v[0:1]
	s_mov_b32 m0, s75
	v_lshl_add_u64 v[224:225], s[80:81], 0, v[130:131]
	global_load_lds_dwordx4 v[222:223], off
	s_add_i32 m0, s75, 0x2000
	v_lshl_add_u64 v[226:227], s[58:59], 0, v[134:135]
	global_load_lds_dwordx4 v[224:225], off
	v_lshl_add_u64 v[228:229], s[58:59], 0, v[132:133]
	s_waitcnt vmcnt(6)
	s_waitcnt lgkmcnt(0)
	s_barrier
	s_setprio 1
	s_waitcnt lgkmcnt(0)
	v_mfma_f32_16x16x32_bf16 v[62:65], v[140:143], v[176:179], v[62:65]
	v_mfma_f32_16x16x32_bf16 v[58:61], v[152:155], v[176:179], v[58:61]
	v_mfma_f32_16x16x32_bf16 v[46:49], v[140:143], v[184:187], v[46:49]
	v_mfma_f32_16x16x32_bf16 v[42:45], v[152:155], v[184:187], v[42:45]
	v_mfma_f32_16x16x32_bf16 v[30:33], v[140:143], v[204:207], v[30:33]
	v_mfma_f32_16x16x32_bf16 v[26:29], v[152:155], v[204:207], v[26:29]
	v_mfma_f32_16x16x32_bf16 v[14:17], v[140:143], v[212:215], v[14:17]
	v_mfma_f32_16x16x32_bf16 v[10:13], v[152:155], v[212:215], v[10:13]
	v_mfma_f32_16x16x32_bf16 v[62:65], v[148:151], v[180:183], v[62:65]
	v_mfma_f32_16x16x32_bf16 v[58:61], v[156:159], v[180:183], v[58:61]
	v_mfma_f32_16x16x32_bf16 v[46:49], v[148:151], v[200:203], v[46:49]
	v_mfma_f32_16x16x32_bf16 v[42:45], v[156:159], v[200:203], v[42:45]
	v_mfma_f32_16x16x32_bf16 v[30:33], v[148:151], v[208:211], v[30:33]
	v_mfma_f32_16x16x32_bf16 v[26:29], v[156:159], v[208:211], v[26:29]
	v_mfma_f32_16x16x32_bf16 v[14:17], v[148:151], v[216:219], v[14:17]
	v_mfma_f32_16x16x32_bf16 v[10:13], v[156:159], v[216:219], v[10:13]
	s_setprio 0
	s_setprio 1
	v_mfma_f32_16x16x32_bf16 v[54:57], v[160:163], v[176:179], v[54:57]
	v_mfma_f32_16x16x32_bf16 v[50:53], v[168:171], v[176:179], v[50:53]
	v_mfma_f32_16x16x32_bf16 v[38:41], v[160:163], v[184:187], v[38:41]
	v_mfma_f32_16x16x32_bf16 v[34:37], v[168:171], v[184:187], v[34:37]
	v_mfma_f32_16x16x32_bf16 v[22:25], v[160:163], v[204:207], v[22:25]
	v_mfma_f32_16x16x32_bf16 v[18:21], v[168:171], v[204:207], v[18:21]
	v_mfma_f32_16x16x32_bf16 v[6:9], v[160:163], v[212:215], v[6:9]
	v_mfma_f32_16x16x32_bf16 v[2:5], v[168:171], v[212:215], v[2:5]
	v_mfma_f32_16x16x32_bf16 v[54:57], v[164:167], v[180:183], v[54:57]
	v_mfma_f32_16x16x32_bf16 v[50:53], v[172:175], v[180:183], v[50:53]
	v_mfma_f32_16x16x32_bf16 v[38:41], v[164:167], v[200:203], v[38:41]
	v_mfma_f32_16x16x32_bf16 v[34:37], v[172:175], v[200:203], v[34:37]
	v_mfma_f32_16x16x32_bf16 v[22:25], v[164:167], v[208:211], v[22:25]
	v_mfma_f32_16x16x32_bf16 v[18:21], v[172:175], v[208:211], v[18:21]
	v_mfma_f32_16x16x32_bf16 v[6:9], v[164:167], v[216:219], v[6:9]
	v_mfma_f32_16x16x32_bf16 v[2:5], v[172:175], v[216:219], v[2:5]
	s_setprio 0
	s_add_i32 s75, 0, 0x18000
	s_add_i32 s78, 0, 0x1c000
	v_add_u32_e32 v156, s75, v146
	v_add_u32_e32 v172, s78, v146
	ds_read_b128 v[140:143], v156
	ds_read_b128 v[148:151], v156 offset:1024
	ds_read_b128 v[152:155], v156 offset:2048
	ds_read_b128 v[156:159], v156 offset:3072
	ds_read_b128 v[160:163], v172
	ds_read_b128 v[164:167], v172 offset:1024
	ds_read_b128 v[168:171], v172 offset:2048
	ds_read_b128 v[172:175], v172 offset:3072
	s_add_u32 s58, s58, s2
	s_addc_u32 s59, s59, s3
	s_mov_b32 m0, s27
	v_lshl_add_u64 v[230:231], s[58:59], 0, v[134:135]
	s_nop 0
	global_load_lds_dwordx4 v[226:227], off
	s_mov_b32 m0, s30
	s_nop 0
	global_load_lds_dwordx4 v[228:229], off
	s_mov_b32 m0, s31
	s_nop 0
	global_load_lds_dwordx4 v[230:231], off
	v_lshl_add_u64 v[230:231], s[58:59], 0, v[132:133]
	s_mov_b32 m0, s53
	s_nop 0
	global_load_lds_dwordx4 v[230:231], off
	ds_read_b128 v[176:179], v147 offset:32768
	ds_read_b128 v[180:183], v147 offset:33792
	ds_read_b128 v[184:187], v147 offset:34816
	ds_read_b128 v[200:203], v147 offset:35840
	ds_read_b128 v[204:207], v147 offset:36864
	ds_read_b128 v[208:211], v147 offset:37888
	ds_read_b128 v[212:215], v147 offset:38912
	ds_read_b128 v[216:219], v147 offset:39936
	s_waitcnt vmcnt(8)
	s_waitcnt lgkmcnt(0)
	s_barrier
	s_setprio 1
	s_waitcnt lgkmcnt(0)
	v_mfma_f32_16x16x32_bf16 v[122:125], v[140:143], v[176:179], v[122:125]
	v_mfma_f32_16x16x32_bf16 v[126:129], v[152:155], v[176:179], v[126:129]
	v_mfma_f32_16x16x32_bf16 v[110:113], v[140:143], v[184:187], v[110:113]
	v_mfma_f32_16x16x32_bf16 v[106:109], v[152:155], v[184:187], v[106:109]
	v_mfma_f32_16x16x32_bf16 v[94:97], v[140:143], v[204:207], v[94:97]
	v_mfma_f32_16x16x32_bf16 v[90:93], v[152:155], v[204:207], v[90:93]
	v_mfma_f32_16x16x32_bf16 v[78:81], v[140:143], v[212:215], v[78:81]
	v_mfma_f32_16x16x32_bf16 v[74:77], v[152:155], v[212:215], v[74:77]
	v_mfma_f32_16x16x32_bf16 v[122:125], v[148:151], v[180:183], v[122:125]
	v_mfma_f32_16x16x32_bf16 v[126:129], v[156:159], v[180:183], v[126:129]
	v_mfma_f32_16x16x32_bf16 v[110:113], v[148:151], v[200:203], v[110:113]
	v_mfma_f32_16x16x32_bf16 v[106:109], v[156:159], v[200:203], v[106:109]
	v_mfma_f32_16x16x32_bf16 v[94:97], v[148:151], v[208:211], v[94:97]
	v_mfma_f32_16x16x32_bf16 v[90:93], v[156:159], v[208:211], v[90:93]
	v_mfma_f32_16x16x32_bf16 v[78:81], v[148:151], v[216:219], v[78:81]
	v_mfma_f32_16x16x32_bf16 v[74:77], v[156:159], v[216:219], v[74:77]
	s_setprio 0
	s_setprio 1
	v_mfma_f32_16x16x32_bf16 v[118:121], v[160:163], v[176:179], v[118:121]
	v_mfma_f32_16x16x32_bf16 v[114:117], v[168:171], v[176:179], v[114:117]
	v_mfma_f32_16x16x32_bf16 v[102:105], v[160:163], v[184:187], v[102:105]
	v_mfma_f32_16x16x32_bf16 v[98:101], v[168:171], v[184:187], v[98:101]
	v_mfma_f32_16x16x32_bf16 v[86:89], v[160:163], v[204:207], v[86:89]
	v_mfma_f32_16x16x32_bf16 v[82:85], v[168:171], v[204:207], v[82:85]
	v_mfma_f32_16x16x32_bf16 v[70:73], v[160:163], v[212:215], v[70:73]
	v_mfma_f32_16x16x32_bf16 v[66:69], v[168:171], v[212:215], v[66:69]
	v_mfma_f32_16x16x32_bf16 v[118:121], v[164:167], v[180:183], v[118:121]
	v_mfma_f32_16x16x32_bf16 v[114:117], v[172:175], v[180:183], v[114:117]
	v_mfma_f32_16x16x32_bf16 v[102:105], v[164:167], v[200:203], v[102:105]
	v_mfma_f32_16x16x32_bf16 v[98:101], v[172:175], v[200:203], v[98:101]
	v_mfma_f32_16x16x32_bf16 v[86:89], v[164:167], v[208:211], v[86:89]
	v_mfma_f32_16x16x32_bf16 v[82:85], v[172:175], v[208:211], v[82:85]
	v_mfma_f32_16x16x32_bf16 v[70:73], v[164:167], v[216:219], v[70:73]
	v_mfma_f32_16x16x32_bf16 v[66:69], v[172:175], v[216:219], v[66:69]
	s_setprio 0
	s_add_i32 s58, s75, s5
	v_lshl_add_u64 v[188:189], v[188:189], 0, s[24:25]
	s_mov_b32 m0, s58
	ds_read_b128 v[176:179], v147 offset:49152
	ds_read_b128 v[180:183], v147 offset:50176
	ds_read_b128 v[184:187], v147 offset:51200
	ds_read_b128 v[200:203], v147 offset:52224
	ds_read_b128 v[204:207], v147 offset:53248
	ds_read_b128 v[208:211], v147 offset:54272
	ds_read_b128 v[212:215], v147 offset:55296
	ds_read_b128 v[216:219], v147 offset:56320
	global_load_lds_dwordx4 v[188:189], off
	v_lshl_add_u64 v[188:189], v[220:221], 0, s[24:25]
	s_add_i32 m0, s58, 0x2000
	s_add_i32 s58, s78, s5
	global_load_lds_dwordx4 v[188:189], off
	v_lshl_add_u64 v[188:189], v[222:223], 0, s[24:25]
	s_mov_b32 m0, s58
	s_nop 0
	global_load_lds_dwordx4 v[188:189], off
	v_lshl_add_u64 v[188:189], v[224:225], 0, s[24:25]
	s_add_i32 m0, s58, 0x2000
	s_nop 0
	global_load_lds_dwordx4 v[188:189], off
	s_waitcnt vmcnt(6)
	s_waitcnt lgkmcnt(0)
	s_barrier
	s_setprio 1
	s_waitcnt lgkmcnt(0)
	v_mfma_f32_16x16x32_bf16 v[62:65], v[140:143], v[176:179], v[62:65]
	v_mfma_f32_16x16x32_bf16 v[58:61], v[152:155], v[176:179], v[58:61]
	v_mfma_f32_16x16x32_bf16 v[46:49], v[140:143], v[184:187], v[46:49]
	v_mfma_f32_16x16x32_bf16 v[42:45], v[152:155], v[184:187], v[42:45]
	v_mfma_f32_16x16x32_bf16 v[30:33], v[140:143], v[204:207], v[30:33]
	v_mfma_f32_16x16x32_bf16 v[26:29], v[152:155], v[204:207], v[26:29]
	v_mfma_f32_16x16x32_bf16 v[14:17], v[140:143], v[212:215], v[14:17]
	v_mfma_f32_16x16x32_bf16 v[10:13], v[152:155], v[212:215], v[10:13]
	v_mfma_f32_16x16x32_bf16 v[62:65], v[148:151], v[180:183], v[62:65]
	v_mfma_f32_16x16x32_bf16 v[58:61], v[156:159], v[180:183], v[58:61]
	v_mfma_f32_16x16x32_bf16 v[46:49], v[148:151], v[200:203], v[46:49]
	v_mfma_f32_16x16x32_bf16 v[42:45], v[156:159], v[200:203], v[42:45]
	v_mfma_f32_16x16x32_bf16 v[30:33], v[148:151], v[208:211], v[30:33]
	v_mfma_f32_16x16x32_bf16 v[26:29], v[156:159], v[208:211], v[26:29]
	v_mfma_f32_16x16x32_bf16 v[14:17], v[148:151], v[216:219], v[14:17]
	v_mfma_f32_16x16x32_bf16 v[10:13], v[156:159], v[216:219], v[10:13]
	s_setprio 0
	s_setprio 1
	v_mfma_f32_16x16x32_bf16 v[54:57], v[160:163], v[176:179], v[54:57]
	v_mfma_f32_16x16x32_bf16 v[50:53], v[168:171], v[176:179], v[50:53]
	v_mfma_f32_16x16x32_bf16 v[38:41], v[160:163], v[184:187], v[38:41]
	v_mfma_f32_16x16x32_bf16 v[34:37], v[168:171], v[184:187], v[34:37]
	v_mfma_f32_16x16x32_bf16 v[22:25], v[160:163], v[204:207], v[22:25]
	v_mfma_f32_16x16x32_bf16 v[18:21], v[168:171], v[204:207], v[18:21]
	v_mfma_f32_16x16x32_bf16 v[6:9], v[160:163], v[212:215], v[6:9]
	v_mfma_f32_16x16x32_bf16 v[2:5], v[168:171], v[212:215], v[2:5]
	v_mfma_f32_16x16x32_bf16 v[54:57], v[164:167], v[180:183], v[54:57]
	v_mfma_f32_16x16x32_bf16 v[50:53], v[172:175], v[180:183], v[50:53]
	v_mfma_f32_16x16x32_bf16 v[38:41], v[164:167], v[200:203], v[38:41]
	v_mfma_f32_16x16x32_bf16 v[34:37], v[172:175], v[200:203], v[34:37]
	v_mfma_f32_16x16x32_bf16 v[22:25], v[164:167], v[208:211], v[22:25]
	v_mfma_f32_16x16x32_bf16 v[18:21], v[172:175], v[208:211], v[18:21]
	v_mfma_f32_16x16x32_bf16 v[6:9], v[164:167], v[216:219], v[6:9]
	v_mfma_f32_16x16x32_bf16 v[2:5], v[172:175], v[216:219], v[2:5]
	s_setprio 0
	s_add_u32 s56, s56, 0x100
	s_addc_u32 s57, s57, 0
	s_add_u32 s51, s51, 0x100
	s_addc_u32 s55, s55, 0
	s_cmp_ge_i32 s74, s61
	s_mov_b32 s58, s74
	s_cbranch_scc0 .LBB0_230
	s_branch .Lmy_post230
	s_nop 0
	s_nop 0
	s_nop 0
	s_nop 0
	s_nop 0
	s_nop 0
	s_nop 0
	s_nop 0
	s_nop 0
	s_nop 0
	s_nop 0
	s_nop 0
	s_nop 0
	s_nop 0
	s_nop 0
	s_nop 0
	s_nop 0
	s_nop 0
	s_nop 0
	s_nop 0
	s_nop 0
	s_nop 0
	s_nop 0
	s_nop 0
	s_nop 0
	s_nop 0
	s_nop 0
	s_nop 0
	s_nop 0
	s_nop 0
	s_nop 0
	s_nop 0
	s_nop 0
	s_nop 0
	s_nop 0
	s_nop 0
	s_nop 0
	s_nop 0
	s_nop 0
	s_nop 0
	s_nop 0
	s_nop 0
	s_nop 0
	s_nop 0
	s_nop 0
	s_nop 0
	s_nop 0
	s_nop 0
	s_nop 0
	s_nop 0
	s_nop 0
	s_nop 0
	s_nop 0
	s_nop 0
	s_nop 0
	s_nop 0
	s_nop 0
	s_nop 0
	s_nop 0
.Lmy_q230:
	s_add_i32 s74, s58, 2
	s_add_u32 s75, s56, 0x80
	s_addc_u32 s59, s57, 0
	s_add_i32 s78, 0, 0x10000
	s_cmp_eq_u32 s66, s58
	s_cselect_b32 s59, s29, s59
	s_cselect_b32 s58, s50, s75
	s_cselect_b32 s81, s45, s55
	s_cselect_b32 s80, s44, s51
	s_add_i32 s75, 0, 0x14000
	v_add_u32_e32 v156, s78, v146
	v_add_u32_e32 v172, s75, v146
	ds_read_b128 v[140:143], v156
	ds_read_b128 v[148:151], v156 offset:1024
	ds_read_b128 v[152:155], v156 offset:2048
	ds_read_b128 v[156:159], v156 offset:3072
	ds_read_b128 v[160:163], v172
	ds_read_b128 v[164:167], v172 offset:1024
	ds_read_b128 v[168:171], v172 offset:2048
	ds_read_b128 v[172:175], v172 offset:3072
	v_lshl_add_u64 v[188:189], s[56:57], 0, v[134:135]
	s_mov_b32 m0, s64
	s_nop 0
	global_load_lds_dwordx4 v[188:189], off
	v_lshl_add_u64 v[188:189], s[56:57], 0, v[132:133]
	s_mov_b32 m0, s65
	s_nop 0
	global_load_lds_dwordx4 v[188:189], off
	v_lshl_add_u64 v[188:189], s[56:57], 0, v[136:137]
	s_add_i32 m0, s27, 0xc000
	s_nop 0
	global_load_lds_dwordx4 v[188:189], off
	v_lshl_add_u64 v[188:189], s[56:57], 0, v[138:139]
	s_add_i32 m0, s27, 0xe000
	s_nop 0
	global_load_lds_dwordx4 v[188:189], off
	ds_read_b128 v[176:179], v147
	ds_read_b128 v[180:183], v147 offset:1024
	ds_read_b128 v[184:187], v147 offset:2048
	ds_read_b128 v[200:203], v147 offset:3072
	ds_read_b128 v[204:207], v147 offset:4096
	ds_read_b128 v[208:211], v147 offset:5120
	ds_read_b128 v[212:215], v147 offset:6144
	ds_read_b128 v[216:219], v147 offset:7168
	s_waitcnt vmcnt(8)
	s_waitcnt lgkmcnt(0)
	s_setprio 1
	s_waitcnt lgkmcnt(0)
	v_mfma_f32_16x16x32_bf16 v[122:125], v[140:143], v[176:179], v[122:125]
	v_mfma_f32_16x16x32_bf16 v[126:129], v[152:155], v[176:179], v[126:129]
	v_mfma_f32_16x16x32_bf16 v[110:113], v[140:143], v[184:187], v[110:113]
	v_mfma_f32_16x16x32_bf16 v[106:109], v[152:155], v[184:187], v[106:109]
	v_mfma_f32_16x16x32_bf16 v[94:97], v[140:143], v[204:207], v[94:97]
	v_mfma_f32_16x16x32_bf16 v[90:93], v[152:155], v[204:207], v[90:93]
	v_mfma_f32_16x16x32_bf16 v[78:81], v[140:143], v[212:215], v[78:81]
	v_mfma_f32_16x16x32_bf16 v[74:77], v[152:155], v[212:215], v[74:77]
	v_mfma_f32_16x16x32_bf16 v[122:125], v[148:151], v[180:183], v[122:125]
	v_mfma_f32_16x16x32_bf16 v[126:129], v[156:159], v[180:183], v[126:129]
	v_mfma_f32_16x16x32_bf16 v[110:113], v[148:151], v[200:203], v[110:113]
	v_mfma_f32_16x16x32_bf16 v[106:109], v[156:159], v[200:203], v[106:109]
	v_mfma_f32_16x16x32_bf16 v[94:97], v[148:151], v[208:211], v[94:97]
	v_mfma_f32_16x16x32_bf16 v[90:93], v[156:159], v[208:211], v[90:93]
	v_mfma_f32_16x16x32_bf16 v[78:81], v[148:151], v[216:219], v[78:81]
	v_mfma_f32_16x16x32_bf16 v[74:77], v[156:159], v[216:219], v[74:77]
	s_setprio 0
	s_setprio 1
	v_mfma_f32_16x16x32_bf16 v[118:121], v[160:163], v[176:179], v[118:121]
	v_mfma_f32_16x16x32_bf16 v[114:117], v[168:171], v[176:179], v[114:117]
	v_mfma_f32_16x16x32_bf16 v[102:105], v[160:163], v[184:187], v[102:105]
	v_mfma_f32_16x16x32_bf16 v[98:101], v[168:171], v[184:187], v[98:101]
	v_mfma_f32_16x16x32_bf16 v[86:89], v[160:163], v[204:207], v[86:89]
	v_mfma_f32_16x16x32_bf16 v[82:85], v[168:171], v[204:207], v[82:85]
	v_mfma_f32_16x16x32_bf16 v[70:73], v[160:163], v[212:215], v[70:73]
	v_mfma_f32_16x16x32_bf16 v[66:69], v[168:171], v[212:215], v[66:69]
	v_mfma_f32_16x16x32_bf16 v[118:121], v[164:167], v[180:183], v[118:121]
	v_mfma_f32_16x16x32_bf16 v[114:117], v[172:175], v[180:183], v[114:117]
	v_mfma_f32_16x16x32_bf16 v[102:105], v[164:167], v[200:203], v[102:105]
	v_mfma_f32_16x16x32_bf16 v[98:101], v[172:175], v[200:203], v[98:101]
	v_mfma_f32_16x16x32_bf16 v[86:89], v[164:167], v[208:211], v[86:89]
	v_mfma_f32_16x16x32_bf16 v[82:85], v[172:175], v[208:211], v[82:85]
	v_mfma_f32_16x16x32_bf16 v[70:73], v[164:167], v[216:219], v[70:73]
	v_mfma_f32_16x16x32_bf16 v[66:69], v[172:175], v[216:219], v[66:69]
	s_setprio 0
	s_barrier
	s_add_i32 s78, s78, s5
	v_lshl_add_u64 v[188:189], s[80:81], 0, v[0:1]
	s_mov_b32 m0, s78
	ds_read_b128 v[176:179], v147 offset:16384
	ds_read_b128 v[180:183], v147 offset:17408
	ds_read_b128 v[184:187], v147 offset:18432
	ds_read_b128 v[200:203], v147 offset:19456
	ds_read_b128 v[204:207], v147 offset:20480
	ds_read_b128 v[208:211], v147 offset:21504
	ds_read_b128 v[212:215], v147 offset:22528
	ds_read_b128 v[216:219], v147 offset:23552
	global_load_lds_dwordx4 v[188:189], off
	s_add_i32 m0, s78, 0x2000
	v_lshl_add_u64 v[220:221], s[80:81], 0, v[130:131]
	s_add_u32 s80, s80, s6
	s_addc_u32 s81, s81, s7
	s_add_i32 s75, s75, s5
	global_load_lds_dwordx4 v[220:221], off
	v_lshl_add_u64 v[222:223], s[80:81], 0, v[0:1]
	s_mov_b32 m0, s75
	v_lshl_add_u64 v[224:225], s[80:81], 0, v[130:131]
	global_load_lds_dwordx4 v[222:223], off
	s_add_i32 m0, s75, 0x2000
	v_lshl_add_u64 v[226:227], s[58:59], 0, v[134:135]
	global_load_lds_dwordx4 v[224:225], off
	v_lshl_add_u64 v[228:229], s[58:59], 0, v[132:133]
	s_waitcnt vmcnt(6)
	s_waitcnt lgkmcnt(0)
	s_setprio 1
	s_waitcnt lgkmcnt(0)
	v_mfma_f32_16x16x32_bf16 v[62:65], v[140:143], v[176:179], v[62:65]
	v_mfma_f32_16x16x32_bf16 v[58:61], v[152:155], v[176:179], v[58:61]
	v_mfma_f32_16x16x32_bf16 v[46:49], v[140:143], v[184:187], v[46:49]
	v_mfma_f32_16x16x32_bf16 v[42:45], v[152:155], v[184:187], v[42:45]
	v_mfma_f32_16x16x32_bf16 v[30:33], v[140:143], v[204:207], v[30:33]
	v_mfma_f32_16x16x32_bf16 v[26:29], v[152:155], v[204:207], v[26:29]
	v_mfma_f32_16x16x32_bf16 v[14:17], v[140:143], v[212:215], v[14:17]
	v_mfma_f32_16x16x32_bf16 v[10:13], v[152:155], v[212:215], v[10:13]
	v_mfma_f32_16x16x32_bf16 v[62:65], v[148:151], v[180:183], v[62:65]
	v_mfma_f32_16x16x32_bf16 v[58:61], v[156:159], v[180:183], v[58:61]
	v_mfma_f32_16x16x32_bf16 v[46:49], v[148:151], v[200:203], v[46:49]
	v_mfma_f32_16x16x32_bf16 v[42:45], v[156:159], v[200:203], v[42:45]
	v_mfma_f32_16x16x32_bf16 v[30:33], v[148:151], v[208:211], v[30:33]
	v_mfma_f32_16x16x32_bf16 v[26:29], v[156:159], v[208:211], v[26:29]
	v_mfma_f32_16x16x32_bf16 v[14:17], v[148:151], v[216:219], v[14:17]
	v_mfma_f32_16x16x32_bf16 v[10:13], v[156:159], v[216:219], v[10:13]
	s_setprio 0
	s_setprio 1
	v_mfma_f32_16x16x32_bf16 v[54:57], v[160:163], v[176:179], v[54:57]
	v_mfma_f32_16x16x32_bf16 v[50:53], v[168:171], v[176:179], v[50:53]
	v_mfma_f32_16x16x32_bf16 v[38:41], v[160:163], v[184:187], v[38:41]
	v_mfma_f32_16x16x32_bf16 v[34:37], v[168:171], v[184:187], v[34:37]
	v_mfma_f32_16x16x32_bf16 v[22:25], v[160:163], v[204:207], v[22:25]
	v_mfma_f32_16x16x32_bf16 v[18:21], v[168:171], v[204:207], v[18:21]
	v_mfma_f32_16x16x32_bf16 v[6:9], v[160:163], v[212:215], v[6:9]
	v_mfma_f32_16x16x32_bf16 v[2:5], v[168:171], v[212:215], v[2:5]
	v_mfma_f32_16x16x32_bf16 v[54:57], v[164:167], v[180:183], v[54:57]
	v_mfma_f32_16x16x32_bf16 v[50:53], v[172:175], v[180:183], v[50:53]
	v_mfma_f32_16x16x32_bf16 v[38:41], v[164:167], v[200:203], v[38:41]
	v_mfma_f32_16x16x32_bf16 v[34:37], v[172:175], v[200:203], v[34:37]
	v_mfma_f32_16x16x32_bf16 v[22:25], v[164:167], v[208:211], v[22:25]
	v_mfma_f32_16x16x32_bf16 v[18:21], v[172:175], v[208:211], v[18:21]
	v_mfma_f32_16x16x32_bf16 v[6:9], v[164:167], v[216:219], v[6:9]
	v_mfma_f32_16x16x32_bf16 v[2:5], v[172:175], v[216:219], v[2:5]
	s_setprio 0
	s_barrier
	s_add_i32 s75, 0, 0x18000
	s_add_i32 s78, 0, 0x1c000
	v_add_u32_e32 v156, s75, v146
	v_add_u32_e32 v172, s78, v146
	ds_read_b128 v[140:143], v156
	ds_read_b128 v[148:151], v156 offset:1024
	ds_read_b128 v[152:155], v156 offset:2048
	ds_read_b128 v[156:159], v156 offset:3072
	ds_read_b128 v[160:163], v172
	ds_read_b128 v[164:167], v172 offset:1024
	ds_read_b128 v[168:171], v172 offset:2048
	ds_read_b128 v[172:175], v172 offset:3072
	s_add_u32 s58, s58, s2
	s_addc_u32 s59, s59, s3
	s_mov_b32 m0, s27
	v_lshl_add_u64 v[230:231], s[58:59], 0, v[134:135]
	s_nop 0
	global_load_lds_dwordx4 v[226:227], off
	s_mov_b32 m0, s30
	s_nop 0
	global_load_lds_dwordx4 v[228:229], off
	s_mov_b32 m0, s31
	s_nop 0
	global_load_lds_dwordx4 v[230:231], off
	v_lshl_add_u64 v[230:231], s[58:59], 0, v[132:133]
	s_mov_b32 m0, s53
	s_nop 0
	global_load_lds_dwordx4 v[230:231], off
	ds_read_b128 v[176:179], v147 offset:32768
	ds_read_b128 v[180:183], v147 offset:33792
	ds_read_b128 v[184:187], v147 offset:34816
	ds_read_b128 v[200:203], v147 offset:35840
	ds_read_b128 v[204:207], v147 offset:36864
	ds_read_b128 v[208:211], v147 offset:37888
	ds_read_b128 v[212:215], v147 offset:38912
	ds_read_b128 v[216:219], v147 offset:39936
	s_waitcnt vmcnt(8)
	s_waitcnt lgkmcnt(0)
	s_setprio 1
	s_waitcnt lgkmcnt(0)
	v_mfma_f32_16x16x32_bf16 v[122:125], v[140:143], v[176:179], v[122:125]
	v_mfma_f32_16x16x32_bf16 v[126:129], v[152:155], v[176:179], v[126:129]
	v_mfma_f32_16x16x32_bf16 v[110:113], v[140:143], v[184:187], v[110:113]
	v_mfma_f32_16x16x32_bf16 v[106:109], v[152:155], v[184:187], v[106:109]
	v_mfma_f32_16x16x32_bf16 v[94:97], v[140:143], v[204:207], v[94:97]
	v_mfma_f32_16x16x32_bf16 v[90:93], v[152:155], v[204:207], v[90:93]
	v_mfma_f32_16x16x32_bf16 v[78:81], v[140:143], v[212:215], v[78:81]
	v_mfma_f32_16x16x32_bf16 v[74:77], v[152:155], v[212:215], v[74:77]
	v_mfma_f32_16x16x32_bf16 v[122:125], v[148:151], v[180:183], v[122:125]
	v_mfma_f32_16x16x32_bf16 v[126:129], v[156:159], v[180:183], v[126:129]
	v_mfma_f32_16x16x32_bf16 v[110:113], v[148:151], v[200:203], v[110:113]
	v_mfma_f32_16x16x32_bf16 v[106:109], v[156:159], v[200:203], v[106:109]
	v_mfma_f32_16x16x32_bf16 v[94:97], v[148:151], v[208:211], v[94:97]
	v_mfma_f32_16x16x32_bf16 v[90:93], v[156:159], v[208:211], v[90:93]
	v_mfma_f32_16x16x32_bf16 v[78:81], v[148:151], v[216:219], v[78:81]
	v_mfma_f32_16x16x32_bf16 v[74:77], v[156:159], v[216:219], v[74:77]
	s_setprio 0
	s_setprio 1
	v_mfma_f32_16x16x32_bf16 v[118:121], v[160:163], v[176:179], v[118:121]
	v_mfma_f32_16x16x32_bf16 v[114:117], v[168:171], v[176:179], v[114:117]
	v_mfma_f32_16x16x32_bf16 v[102:105], v[160:163], v[184:187], v[102:105]
	v_mfma_f32_16x16x32_bf16 v[98:101], v[168:171], v[184:187], v[98:101]
	v_mfma_f32_16x16x32_bf16 v[86:89], v[160:163], v[204:207], v[86:89]
	v_mfma_f32_16x16x32_bf16 v[82:85], v[168:171], v[204:207], v[82:85]
	v_mfma_f32_16x16x32_bf16 v[70:73], v[160:163], v[212:215], v[70:73]
	v_mfma_f32_16x16x32_bf16 v[66:69], v[168:171], v[212:215], v[66:69]
	v_mfma_f32_16x16x32_bf16 v[118:121], v[164:167], v[180:183], v[118:121]
	v_mfma_f32_16x16x32_bf16 v[114:117], v[172:175], v[180:183], v[114:117]
	v_mfma_f32_16x16x32_bf16 v[102:105], v[164:167], v[200:203], v[102:105]
	v_mfma_f32_16x16x32_bf16 v[98:101], v[172:175], v[200:203], v[98:101]
	v_mfma_f32_16x16x32_bf16 v[86:89], v[164:167], v[208:211], v[86:89]
	v_mfma_f32_16x16x32_bf16 v[82:85], v[172:175], v[208:211], v[82:85]
	v_mfma_f32_16x16x32_bf16 v[70:73], v[164:167], v[216:219], v[70:73]
	v_mfma_f32_16x16x32_bf16 v[66:69], v[172:175], v[216:219], v[66:69]
	s_setprio 0
	s_barrier
	s_add_i32 s58, s75, s5
	v_lshl_add_u64 v[188:189], v[188:189], 0, s[24:25]
	s_mov_b32 m0, s58
	ds_read_b128 v[176:179], v147 offset:49152
	ds_read_b128 v[180:183], v147 offset:50176
	ds_read_b128 v[184:187], v147 offset:51200
	ds_read_b128 v[200:203], v147 offset:52224
	ds_read_b128 v[204:207], v147 offset:53248
	ds_read_b128 v[208:211], v147 offset:54272
	ds_read_b128 v[212:215], v147 offset:55296
	ds_read_b128 v[216:219], v147 offset:56320
	global_load_lds_dwordx4 v[188:189], off
	v_lshl_add_u64 v[188:189], v[220:221], 0, s[24:25]
	s_add_i32 m0, s58, 0x2000
	s_add_i32 s58, s78, s5
	global_load_lds_dwordx4 v[188:189], off
	v_lshl_add_u64 v[188:189], v[222:223], 0, s[24:25]
	s_mov_b32 m0, s58
	s_nop 0
	global_load_lds_dwordx4 v[188:189], off
	v_lshl_add_u64 v[188:189], v[224:225], 0, s[24:25]
	s_add_i32 m0, s58, 0x2000
	s_nop 0
	global_load_lds_dwordx4 v[188:189], off
	s_waitcnt vmcnt(6)
	s_waitcnt lgkmcnt(0)
	s_setprio 1
	s_waitcnt lgkmcnt(0)
	v_mfma_f32_16x16x32_bf16 v[62:65], v[140:143], v[176:179], v[62:65]
	v_mfma_f32_16x16x32_bf16 v[58:61], v[152:155], v[176:179], v[58:61]
	v_mfma_f32_16x16x32_bf16 v[46:49], v[140:143], v[184:187], v[46:49]
	v_mfma_f32_16x16x32_bf16 v[42:45], v[152:155], v[184:187], v[42:45]
	v_mfma_f32_16x16x32_bf16 v[30:33], v[140:143], v[204:207], v[30:33]
	v_mfma_f32_16x16x32_bf16 v[26:29], v[152:155], v[204:207], v[26:29]
	v_mfma_f32_16x16x32_bf16 v[14:17], v[140:143], v[212:215], v[14:17]
	v_mfma_f32_16x16x32_bf16 v[10:13], v[152:155], v[212:215], v[10:13]
	v_mfma_f32_16x16x32_bf16 v[62:65], v[148:151], v[180:183], v[62:65]
	v_mfma_f32_16x16x32_bf16 v[58:61], v[156:159], v[180:183], v[58:61]
	v_mfma_f32_16x16x32_bf16 v[46:49], v[148:151], v[200:203], v[46:49]
	v_mfma_f32_16x16x32_bf16 v[42:45], v[156:159], v[200:203], v[42:45]
	v_mfma_f32_16x16x32_bf16 v[30:33], v[148:151], v[208:211], v[30:33]
	v_mfma_f32_16x16x32_bf16 v[26:29], v[156:159], v[208:211], v[26:29]
	v_mfma_f32_16x16x32_bf16 v[14:17], v[148:151], v[216:219], v[14:17]
	v_mfma_f32_16x16x32_bf16 v[10:13], v[156:159], v[216:219], v[10:13]
	s_setprio 0
	s_setprio 1
	v_mfma_f32_16x16x32_bf16 v[54:57], v[160:163], v[176:179], v[54:57]
	v_mfma_f32_16x16x32_bf16 v[50:53], v[168:171], v[176:179], v[50:53]
	v_mfma_f32_16x16x32_bf16 v[38:41], v[160:163], v[184:187], v[38:41]
	v_mfma_f32_16x16x32_bf16 v[34:37], v[168:171], v[184:187], v[34:37]
	v_mfma_f32_16x16x32_bf16 v[22:25], v[160:163], v[204:207], v[22:25]
	v_mfma_f32_16x16x32_bf16 v[18:21], v[168:171], v[204:207], v[18:21]
	v_mfma_f32_16x16x32_bf16 v[6:9], v[160:163], v[212:215], v[6:9]
	v_mfma_f32_16x16x32_bf16 v[2:5], v[168:171], v[212:215], v[2:5]
	v_mfma_f32_16x16x32_bf16 v[54:57], v[164:167], v[180:183], v[54:57]
	v_mfma_f32_16x16x32_bf16 v[50:53], v[172:175], v[180:183], v[50:53]
	v_mfma_f32_16x16x32_bf16 v[38:41], v[164:167], v[200:203], v[38:41]
	v_mfma_f32_16x16x32_bf16 v[34:37], v[172:175], v[200:203], v[34:37]
	v_mfma_f32_16x16x32_bf16 v[22:25], v[164:167], v[208:211], v[22:25]
	v_mfma_f32_16x16x32_bf16 v[18:21], v[172:175], v[208:211], v[18:21]
	v_mfma_f32_16x16x32_bf16 v[6:9], v[164:167], v[216:219], v[6:9]
	v_mfma_f32_16x16x32_bf16 v[2:5], v[172:175], v[216:219], v[2:5]
	s_setprio 0
	s_barrier
	s_add_u32 s56, s56, 0x100
	s_addc_u32 s57, s57, 0
	s_add_u32 s51, s51, 0x100
	s_addc_u32 s55, s55, 0
	s_cmp_ge_i32 s74, s61
	s_mov_b32 s58, s74
	s_cbranch_scc0 .Lmy_q230
.Lmy_post230:
	v_readlane_b32 s74, v236, 30
	v_readlane_b32 s75, v236, 31
	s_mov_b32 s78, s76
.LBB0_232:
	s_and_b64 vcc, exec, s[40:41]
	s_cbranch_vccz .LBB0_234
	s_nop 0

.LBB0_250:
	s_or_b64 exec, exec, s[50:51]
	s_andn2_b64 vcc, exec, s[46:47]
	s_mov_b64 s[28:29], -1
	s_cbranch_vccnz .LBB0_225
	s_andn2_b64 vcc, exec, s[38:39]
	s_cbranch_vccnz .LBB0_224
	s_nop 0
	s_branch .LBB0_224
